# static s_setprio 1 for waves 4-7 across the attention core phase (global + neighbourhood) and the conv-mixer core phase, reset at phase end; on top of the hand-written attention loop
# speedup vs baseline: 1.0066x; 1.0025x over previous
.LBB0_468:
	s_cmp_ge_i32 s6, s96
	s_cselect_b64 s[24:25], -1, 0
	s_cmp_lt_i32 s6, s97
	s_cselect_b64 s[26:27], -1, 0
	s_and_b64 s[24:25], s[24:25], s[26:27]
	s_andn2_b64 vcc, exec, s[24:25]
	s_cbranch_vccnz .LBB0_618
	s_cmp_lt_u32 s33, 0x100
	s_cbranch_scc1 .Lcd_noprio
	s_setprio 1
.Lcd_noprio:
	v_readlane_b32 s24, v254, 42
	v_readlane_b32 s25, v254, 43
	s_andn2_b64 vcc, exec, s[24:25]
	s_nop 0
	v_cndmask_b32_e64 v0, 0, 1, s[24:25]
	v_cmp_ne_u32_e64 s[44:45], 1, v0
	s_cbranch_vccnz .LBB0_495
	v_mbcnt_lo_u32_b32 v0, -1, 0
	v_mbcnt_hi_u32_b32 v0, -1, v0
	s_waitcnt lgkmcnt(0)
	v_mov_b32_e32 v1, v144
	v_add_u32_e32 v44, s33, v0
	v_lshlrev_b32_e32 v0, 4, v0
	v_and_b32_e32 v0, 0x3f0, v0
	v_ashrrev_i32_e32 v8, 6, v44
	v_readlane_b32 s19, v254, 44
	v_lshl_add_u64 v[48:49], s[88:89], 0, v[0:1]
	v_mov_b32_e32 v2, v144
	v_add_u32_e32 v0, s19, v8
	v_mov_b32_e32 v3, v144
	v_cmp_gt_i32_e32 vcc, s15, v8
	v_cmp_gt_u32_e64 s[46:47], s14, v0
	v_mov_b32_e32 v0, v144
	v_mov_b64_e32 v[6:7], v[2:3]
	s_and_b64 s[24:25], vcc, s[46:47]
	v_mov_b64_e32 v[4:5], v[0:1]
	s_and_saveexec_b64 s[46:47], s[24:25]
	v_readlane_b32 s6, v253, 42
	s_cbranch_execz .LBB0_472
	s_nop 0
	v_subrev_u32_e32 v4, s6, v8
	v_add_u32_e32 v4, 0xffb1, v4
	v_ashrrev_i32_e32 v5, 31, v4
	v_lshlrev_b64 v[4:5], 10, v[4:5]
	v_lshl_add_u64 v[4:5], v[48:49], 0, v[4:5]
	global_load_dwordx4 v[4:7], v[4:5], off

.LBB0_551:
	s_setprio 0
	s_add_i32 s6, s76, 4
	v_readlane_b32 s78, v253, 57
	s_cmp_ge_i32 s6, s97
	v_readlane_b32 s79, v253, 58
	s_cbranch_scc1 .LBB0_618
	v_readlane_b32 s24, v252, 38
	v_readlane_b32 s25, v252, 39
	s_mov_b64 s[44:45], -1
	s_and_b64 vcc, exec, s[24:25]
	s_cbranch_vccz .LBB0_606
	s_waitcnt vmcnt(0)
	s_waitcnt vmcnt(0) lgkmcnt(0)
	s_barrier
	s_mov_b64 s[44:45], exec
	v_readlane_b32 s24, v252, 11
	v_readlane_b32 s25, v252, 12
	s_and_b64 s[24:25], s[44:45], s[24:25]
	s_mov_b64 exec, s[24:25]
	s_cbranch_execz .LBB0_605
	v_readlane_b32 s6, v253, 50
	s_waitcnt vmcnt(0) expcnt(0) lgkmcnt(0)
	s_nop 0
	v_mov_b32_e32 v0, s6
	ds_read_b32 v2, v0
	v_readlane_b32 s6, v253, 51
	s_waitcnt lgkmcnt(0)
	v_cmp_ne_u32_e32 vcc, 0, v2
	v_mov_b32_e32 v0, s6
	ds_read_b32 v0, v0
	s_cbranch_vccnz .LBB0_569
	s_mov_b32 s6, 1
	s_branch .LBB0_557

.LBB0_732:
	s_lshr_b32 s6, s19, 5
	s_lshl_b32 s44, s6, 11
	s_bfe_u32 s25, s19, 0x10004
	s_lshl_b32 s6, s6, 1
	s_or_b32 s6, s6, s25
	s_lshl_b64 s[42:43], s[6:7], 18
	s_sub_i32 s6, 0x3ff, s24
	s_lshl_b32 s30, s6, 9
	v_mbcnt_lo_u32_b32 v34, -1, 0
	v_mbcnt_hi_u32_b32 v34, -1, v34
	s_lshr_b32 s26, s6, 5
	v_add_u32_e32 v18, s33, v34
	v_and_b32_e32 v35, 31, v34
	s_and_b32 s30, s30, 0x600
	s_lshl_b32 s28, s25, 7
	v_readfirstlane_b32 s25, v18
	s_lshl_b32 s27, s26, 11
	v_or_b32_e32 v16, s30, v35
	s_andn2_b32 s25, s25, 63
	v_or_b32_e32 v16, s27, v16
	s_bfe_u32 s29, s6, 0x10004
	v_add_u32_e32 v200, s25, v16
	s_lshl_b32 s6, s6, 4
	v_ashrrev_i32_e32 v201, 31, v200
	s_lshl_b32 s25, s29, 8
	s_and_b32 s6, s6, 0xc0
	v_lshlrev_b64 v[16:17], 10, v[200:201]
	s_or_b32 s25, s25, s6
	v_lshl_add_u64 v[16:17], s[88:89], 0, v[16:17]
	s_lshl_b32 s6, s25, 1
	v_lshl_add_u64 v[26:27], v[16:17], 0, s[6:7]
	v_ashrrev_i32_e32 v28, 3, v18
	s_lshl_b32 s6, s26, 1
	v_add_u32_e32 v16, s27, v28
	s_or_b32 s6, s6, s29
	s_ashr_i32 s45, s44, 31
	v_ashrrev_i32_e32 v17, 31, v16
	s_lshl_b64 s[26:27], s[6:7], 18
	v_readlane_b32 s6, v254, 49
	v_lshlrev_b64 v[16:17], 8, v[16:17]
	v_ashrrev_i32_e32 v29, 31, v28
	s_add_u32 s26, s6, s26
	v_readlane_b32 s6, v254, 50
	s_addc_u32 s27, s6, s27
	v_lshlrev_b64 v[30:31], 12, v[28:29]
	v_lshl_add_u64 v[16:17], s[10:11], 0, v[16:17]
	s_lshl_b32 s6, s29, 7
	v_lshlrev_b32_e32 v20, 4, v34
	v_bfe_u32 v145, v34, 5, 1
	v_lshl_add_u64 v[18:19], s[26:27], 0, v[30:31]
	v_lshl_add_u64 v[16:17], v[16:17], 0, s[6:7]
	v_and_b32_e32 v32, 0x70, v20
	v_mov_b32_e32 v33, v144
	v_mov_b32_e32 v205, v144
	v_lshlrev_b32_e32 v204, 4, v145
	v_lshl_add_u64 v[16:17], v[16:17], 0, v[32:33]
	v_lshl_add_u64 v[22:23], v[18:19], 0, v[32:33]
	v_lshl_add_u64 v[26:27], v[26:27], 0, v[204:205]
	s_mov_b32 s26, 0x8000
	global_load_dwordx4 v[18:21], v[16:17], off
	s_nop 0
	global_load_dwordx4 v[22:25], v[22:23], off
	s_nop 0
	global_load_dwordx4 v[170:173], v[26:27], off
	global_load_dwordx4 v[158:161], v[26:27], off offset:32
	global_load_dwordx4 v[154:157], v[26:27], off offset:64
	global_load_dwordx4 v[146:149], v[26:27], off offset:96
	v_add_co_u32_e32 v26, vcc, s26, v26
	v_lshlrev_b32_e32 v17, 1, v34
	s_nop 0
	v_addc_co_u32_e32 v27, vcc, 0, v27, vcc
	global_load_dwordx4 v[174:177], v[26:27], off
	global_load_dwordx4 v[166:169], v[26:27], off offset:32
	global_load_dwordx4 v[162:165], v[26:27], off offset:64
	global_load_dwordx4 v[150:153], v[26:27], off offset:96
	v_lshrrev_b32_e32 v33, 1, v34
	v_and_b32_e32 v34, 19, v34
	v_and_b32_e32 v17, 8, v17
	v_and_b32_e32 v33, 4, v33
	v_or3_b32 v17, v17, v34, v33
	v_mul_lo_u32 v33, v28, s31
	v_lshl_add_u64 v[28:29], v[28:29], 0, s[44:45]
	v_lshlrev_b64 v[26:27], 8, v[28:29]
	v_readlane_b32 s26, v253, 44
	v_or3_b32 v26, v26, s28, v32
	v_readlane_b32 s27, v253, 45
	v_lshl_add_u64 v[28:29], s[42:43], 0, v[30:31]
	v_mov_b32_e32 v16, 0
	v_lshl_add_u64 v[206:207], s[26:27], 0, v[26:27]
	v_readlane_b32 s26, v253, 47
	v_add3_u32 v222, 0, v33, v32
	v_or_b32_e32 v28, v28, v32
	v_readlane_b32 s27, v253, 48
	s_mov_b32 s6, 1
	v_mul_u32_u24_e32 v220, 0x90, v35
	v_mul_u32_u24_e32 v221, 0x90, v17
	v_lshl_add_u64 v[208:209], s[26:27], 0, v[28:29]
	global_load_dwordx4 v[182:185], v[206:207], off
	global_load_dwordx4 v[178:181], v[208:209], off
	s_mov_b64 s[26:27], 0x4000
	v_lshl_add_u64 v[206:207], v[206:207], 0, s[26:27]
	v_lshl_add_u64 v[208:209], v[208:209], 0, s[0:1]
	s_barrier
	v_mov_b32_e32 v17, v16
	v_mov_b32_e32 v26, v16
	v_mov_b32_e32 v27, v16
	v_mov_b32_e32 v28, v16
	v_mov_b32_e32 v29, v16
	v_mov_b32_e32 v30, v16
	v_mov_b32_e32 v31, v16
	v_mov_b32_e32 v32, v16
	s_waitcnt vmcnt(11)
	ds_write_b128 v222, v[18:21]
	s_waitcnt vmcnt(10)
	ds_write_b128 v222, v[22:25] offset:9216
	v_mov_b32_e32 v18, v16
	v_mov_b32_e32 v19, v16
	v_mov_b32_e32 v20, v16
	v_mov_b32_e32 v21, v16
	v_mov_b32_e32 v22, v16
	v_mov_b32_e32 v23, v16
	v_mov_b32_e32 v24, v16
	v_mov_b32_e32 v25, v16
	v_mov_b32_e32 v33, v16
	v_mov_b32_e32 v34, v16
	v_mov_b32_e32 v35, v16
	v_mov_b32_e32 v36, v16
	v_mov_b32_e32 v37, v16
	v_mov_b32_e32 v38, v16
	v_mov_b32_e32 v39, v16
	v_mov_b32_e32 v40, v16
	v_mov_b32_e32 v41, v16
	v_mov_b32_e32 v42, v16
	v_mov_b32_e32 v43, v16
	v_mov_b32_e32 v44, v16
	v_mov_b32_e32 v45, v16
	v_mov_b32_e32 v46, v16
	v_mov_b32_e32 v47, v16
	v_mov_b32_e32 v48, v16
	v_mov_b32_e32 v49, v16
	v_mov_b32_e32 v50, v16
	v_mov_b32_e32 v51, v16
	v_mov_b32_e32 v52, v16
	v_mov_b32_e32 v53, v16
	v_mov_b32_e32 v54, v16
	v_mov_b32_e32 v55, v16
	v_mov_b32_e32 v56, v16
	v_mov_b32_e32 v57, v16
	v_mov_b32_e32 v58, v16
	v_mov_b32_e32 v59, v16
	v_mov_b32_e32 v60, v16
	v_mov_b32_e32 v61, v16
	v_mov_b32_e32 v62, v16
	v_mov_b32_e32 v63, v16
	v_mov_b32_e32 v64, v16
	v_mov_b32_e32 v65, v16
	v_mov_b32_e32 v66, v16
	v_mov_b32_e32 v67, v16
	v_mov_b32_e32 v68, v16
	v_mov_b32_e32 v69, v16
	v_mov_b32_e32 v70, v16
	v_mov_b32_e32 v71, v16
	v_mov_b32_e32 v72, v16
	v_mov_b32_e32 v73, v16
	v_mov_b32_e32 v74, v16
	v_mov_b32_e32 v75, v16
	v_mov_b32_e32 v76, v16
	v_mov_b32_e32 v77, v16
	v_mov_b32_e32 v78, v16
	v_mov_b32_e32 v79, v16
	v_mov_b32_e32 v202, v16
	v_mov_b32_e32 v203, v16
	s_waitcnt lgkmcnt(0)
	s_barrier
	v_mov_b32_e32 v186, 0
	v_mov_b32_e32 v187, 0
	v_mov_b32_e32 v188, 0
	v_mov_b32_e32 v189, 0
	v_add3_u32 v190, 0, v221, v204
	ds_read_b128 v[224:227], v190
	ds_read_b128 v[228:231], v190 offset:4608
	ds_read_b128 v[232:235], v190 offset:32
	ds_read_b128 v[236:239], v190 offset:4640
	ds_read_b128 v[240:243], v190 offset:64
	ds_read_b128 v[244:247], v190 offset:4672
	ds_read_b128 v[248:251], v190 offset:96
	ds_read_b128 v[192:195], v190 offset:4704
	s_waitcnt vmcnt(0)
	ds_write_b128 v222, v[182:185] offset:18432
	ds_write_b128 v222, v[178:181] offset:27648
	s_mov_b32 s100, 0
	s_mov_b32 s101, 0x4800
	s_mov_b32 s26, 0x9000
	s_mov_b32 s6, 0
	s_mov_b64 s[28:29], 0x4000
	s_cmp_lt_u32 s33, 0x100
	s_cbranch_scc1 .Lag_noprio
	s_setprio 1
.Lag_noprio:
.Lag_loop:
	v_add3_u32 v191, s100, v220, v204
	v_add3_u32 v190, s101, v221, v204
	v_add_u32_e32 v196, s26, v222
	s_waitcnt lgkmcnt(9)
	v_mfma_f32_32x32x16_bf16 v[112:127], v[224:227], v[170:173], v[0:15]
	v_mfma_f32_32x32x16_bf16 v[80:95], v[224:227], v[174:177], v[0:15]
	ds_read_b128 v[224:227], v191 offset:9216
	s_waitcnt lgkmcnt(9)
	v_mfma_f32_32x32x16_bf16 v[128:143], v[228:231], v[170:173], v[0:15]
	v_mfma_f32_32x32x16_bf16 v[96:111], v[228:231], v[174:177], v[0:15]
	ds_read_b128 v[228:231], v191 offset:13824
	s_waitcnt lgkmcnt(9)
	v_mfma_f32_32x32x16_bf16 v[112:127], v[232:235], v[158:161], v[112:127]
	v_mfma_f32_32x32x16_bf16 v[80:95], v[232:235], v[166:169], v[80:95]
	ds_read_b128 v[232:235], v191 offset:9248
	s_waitcnt lgkmcnt(9)
	v_mfma_f32_32x32x16_bf16 v[128:143], v[236:239], v[158:161], v[128:143]
	v_mfma_f32_32x32x16_bf16 v[96:111], v[236:239], v[166:169], v[96:111]
	ds_read_b128 v[236:239], v191 offset:13856
	s_waitcnt lgkmcnt(9)
	v_mfma_f32_32x32x16_bf16 v[112:127], v[240:243], v[154:157], v[112:127]
	v_mfma_f32_32x32x16_bf16 v[80:95], v[240:243], v[162:165], v[80:95]
	ds_read_b128 v[240:243], v191 offset:9280
	s_waitcnt lgkmcnt(9)
	v_mfma_f32_32x32x16_bf16 v[128:143], v[244:247], v[154:157], v[128:143]
	v_mfma_f32_32x32x16_bf16 v[96:111], v[244:247], v[162:165], v[96:111]
	ds_read_b128 v[244:247], v191 offset:13888
	s_waitcnt lgkmcnt(9)
	v_mfma_f32_32x32x16_bf16 v[112:127], v[248:251], v[146:149], v[112:127]
	v_mfma_f32_32x32x16_bf16 v[80:95], v[248:251], v[150:153], v[80:95]
	ds_read_b128 v[248:251], v191 offset:9312
	s_waitcnt lgkmcnt(9)
	v_mfma_f32_32x32x16_bf16 v[128:143], v[192:195], v[146:149], v[128:143]
	v_mfma_f32_32x32x16_bf16 v[96:111], v[192:195], v[150:153], v[96:111]
	ds_read_b128 v[192:195], v191 offset:13920
	global_load_dwordx4 v[182:185], v[206:207], off
	global_load_dwordx4 v[178:181], v[208:209], off
	v_lshl_add_u64 v[206:207], v[206:207], 0, s[28:29]
	v_lshl_add_u64 v[208:209], v[208:209], 0, s[0:1]
	s_cmp_lt_u32 s33, 0x100
	s_cbranch_scc1 .Lag_nobar_b
	s_barrier

.LBB0_754:
	s_setprio 0
	s_add_i32 s6, s76, 4
	s_cmp_ge_i32 s6, s97
	s_cbranch_scc1 .LBB0_821
	v_readlane_b32 s24, v252, 38
	v_readlane_b32 s25, v252, 39
	s_mov_b64 s[42:43], -1
	s_and_b64 vcc, exec, s[24:25]
	s_cbranch_vccz .LBB0_809
	s_waitcnt vmcnt(0)
	s_waitcnt lgkmcnt(0)
	s_barrier
	s_mov_b64 s[42:43], exec
	v_readlane_b32 s24, v252, 11
	v_readlane_b32 s25, v252, 12
	s_and_b64 s[24:25], s[42:43], s[24:25]
	s_mov_b64 exec, s[24:25]
	s_cbranch_execz .LBB0_808
	v_readlane_b32 s6, v253, 50
	s_waitcnt vmcnt(0) expcnt(0) lgkmcnt(0)
	s_nop 0
	v_mov_b32_e32 v0, s6
	ds_read_b32 v2, v0
	v_readlane_b32 s6, v253, 51
	s_waitcnt lgkmcnt(0)
	v_cmp_ne_u32_e32 vcc, 0, v2
	v_mov_b32_e32 v0, s6
	ds_read_b32 v0, v0
	s_cbranch_vccnz .LBB0_772
	s_mov_b32 s6, 1
	s_branch .LBB0_760
